# FFN-up epilogue: the two halo-row loads (disjoint lane halves) no longer serialised by an intermediate vmcnt(0)
# speedup vs baseline: 1.0050x; 1.0030x over previous
; __device__ __forceinline__ unsigned pk2(float lo, float hi) { const f2_t v = {lo, hi}; return __builtin_bit_cast(unsigned, __builtin_convertvector(v, bf2_t)); }
;   __device__ __forceinline__ void operator()(const f32x4 (&acc)[2][2][4][2], int pm, int pn, int wr_, int wc_, int fr_, int fq_, bf16_t* shm, int tid) const {
;     ...
; #pragma unroll
;     for (int ai = 0; ai < 2; ++ai)
; #pragma unroll
;       for (int bj = 0; bj < 2; ++bj)
; #pragma unroll
;         for (int m = 0; m < 4; ++m)
; #pragma unroll
;           for (int n = 0; n < 2; ++n) {
;             const f32x4 v = acc[ai][bj][m][n];
;             u32x2 w; w.x = pk2(v[0], v[1]); w.y = pk2(v[2], v[3]);
;             *(u32x2*)(Us + (ai * 128 + wr * 64 + m * 16 + fr + 1) * USTR + bj * 128 + wc * 32 + n * 16 + fq * 4) = w;
;           }
;     if (tid < 64) {
;       const int after = tid >> 5, c = (tid & 31) * 8;
;       u32x4 hv = {0, 0, 0, 0};
;       if (pm < 256) {
;         if (!after && (pm & 7) != 0) hv = *(const u32x4*)(HU + (long)((pm - 1) * 2 + 1) * 5632 + pn * 256 + c);
;         if (after && ((pm + 1) & 7) != 0) hv = *(const u32x4*)(HU + (long)((pm + 1) * 2) * 5632 + pn * 256 + c);
;       }
;       *(u32x4*)(Us + (after ? 257 : 0) * USTR + c) = hv;
;     }
;     __syncthreads();
;     {
;       const int cg = tid & 15, rs = tid >> 4, f0 = pn * 128 + cg * 8;
;       float wa[3][8], wg[3][8], ba[8], bg[8];
; #pragma unroll
;       for (int t = 0; t < 3; ++t)
; #pragma unroll
;         for (int e = 0; e < 8; e += 4) {
;           const f32x4 x = *(const f32x4*)(cw + t * 5632 + f0 + e), y = *(const f32x4*)(cw + t * 5632 + 2816 + f0 + e);
;           wa[t][e] = x[0]; wa[t][e + 1] = x[1]; wa[t][e + 2] = x[2]; wa[t][e + 3] = x[3];
;           wg[t][e] = y[0]; wg[t][e + 1] = y[1]; wg[t][e + 2] = y[2]; wg[t][e + 3] = y[3];
;         }
; #pragma unroll
;       for (int e = 0; e < 8; e += 4) {
;         const f32x4 x = *(const f32x4*)(cb + f0 + e), y = *(const f32x4*)(cb + 2816 + f0 + e);
;         ba[e] = x[0]; ba[e + 1] = x[1]; ba[e + 2] = x[2]; ba[e + 3] = x[3]; bg[e] = y[0]; bg[e + 1] = y[1]; bg[e + 2] = y[2]; bg[e + 3] = y[3];
;       }
.LBB0_391:
	v_readlane_b32 s10, v250, 0
	s_nop 11
	v_mbcnt_lo_u32_b32 v144, -1, 0
	v_mbcnt_hi_u32_b32 v144, -1, v144
	v_cvt_pk_bf16_f32 v90, v90, v91
	v_and_b32_e32 v0, 15, v144
	v_add_u32_e32 v143, s10, v144
	v_lshrrev_b32_e32 v145, 2, v143
	s_mov_b32 s10, 0xfffffc0
	v_ashrrev_i32_e32 v142, 4, v143
	v_and_or_b32 v145, v145, s10, v0
	s_movk_i32 s10, 0x210
	v_mul_lo_u32 v145, v145, s10
	v_lshlrev_b32_e32 v147, 3, v142
	v_add_u32_e32 v145, 16, v145
	v_and_b32_e32 v146, 0xc0, v143
	v_and_b32_e32 v147, 24, v147
	v_add3_u32 v145, v145, v146, v147
	v_cvt_pk_bf16_f32 v91, v92, v93
	v_add_u32_e32 v92, 0x6000, v145
	v_cvt_pk_bf16_f32 v58, v58, v59
	v_cvt_pk_bf16_f32 v59, v60, v61
	v_cvt_pk_bf16_f32 v50, v50, v51
	v_cvt_pk_bf16_f32 v51, v52, v53
	ds_write2_b64 v92, v[58:59], v[50:51] offset0:194 offset1:198
	v_add_u32_e32 v58, 0x10a10, v145
	v_cvt_pk_bf16_f32 v50, v78, v79
	v_cvt_pk_bf16_f32 v51, v80, v81
	v_cvt_pk_bf16_f32 v52, v74, v75
	v_cvt_pk_bf16_f32 v53, v76, v77
	ds_write2_b64 v58, v[50:51], v[52:53] offset1:4
	v_add_u32_e32 v58, 0x12b10, v145
	v_cvt_pk_bf16_f32 v50, v62, v63
	v_cvt_pk_bf16_f32 v51, v64, v65
	v_cvt_pk_bf16_f32 v52, v54, v55
	v_cvt_pk_bf16_f32 v53, v56, v57
	ds_write2_b64 v58, v[50:51], v[52:53] offset1:4
	v_add_u32_e32 v50, 0x14c10, v145
	v_cvt_pk_bf16_f32 v46, v46, v47
	v_cvt_pk_bf16_f32 v47, v48, v49
	v_cvt_pk_bf16_f32 v42, v42, v43
	v_cvt_pk_bf16_f32 v43, v44, v45
	ds_write2_b64 v50, v[46:47], v[42:43] offset1:4
	v_add_u32_e32 v42, 0x16d10, v145
	v_cvt_pk_bf16_f32 v38, v38, v39
	v_cvt_pk_bf16_f32 v39, v40, v41
	v_cvt_pk_bf16_f32 v34, v34, v35
	v_cvt_pk_bf16_f32 v35, v36, v37
	ds_write2_b64 v42, v[38:39], v[34:35] offset1:4
	v_add_u32_e32 v34, 0x10b10, v145
	v_cvt_pk_bf16_f32 v30, v30, v31
	v_cvt_pk_bf16_f32 v31, v32, v33
	v_cvt_pk_bf16_f32 v26, v26, v27
	v_cvt_pk_bf16_f32 v27, v28, v29
	v_cvt_pk_bf16_f32 v82, v82, v83
	v_cvt_pk_bf16_f32 v83, v84, v85
	ds_write2_b64 v34, v[30:31], v[26:27] offset1:4
	v_add_u32_e32 v26, 0x12c10, v145
	v_cvt_pk_bf16_f32 v22, v22, v23
	v_cvt_pk_bf16_f32 v23, v24, v25
	v_cvt_pk_bf16_f32 v18, v18, v19
	v_cvt_pk_bf16_f32 v19, v20, v21
	ds_write2_b64 v92, v[90:91], v[82:83] offset0:162 offset1:166
	v_cvt_pk_bf16_f32 v82, v106, v107
	v_cvt_pk_bf16_f32 v83, v108, v109
	v_cvt_pk_bf16_f32 v84, v98, v99
	v_cvt_pk_bf16_f32 v85, v100, v101
	ds_write2_b64 v26, v[22:23], v[18:19] offset1:4
	v_add_u32_e32 v18, 0x14d10, v145
	v_cvt_pk_bf16_f32 v14, v14, v15
	v_cvt_pk_bf16_f32 v15, v16, v17
	v_cvt_pk_bf16_f32 v10, v10, v11
	v_cvt_pk_bf16_f32 v11, v12, v13
	v_cvt_pk_bf16_f32 v126, v126, v127
	v_cvt_pk_bf16_f32 v127, v128, v129
	v_cvt_pk_bf16_f32 v122, v122, v123
	v_cvt_pk_bf16_f32 v123, v124, v125
	v_cvt_pk_bf16_f32 v118, v118, v119
	v_cvt_pk_bf16_f32 v119, v120, v121
	v_cvt_pk_bf16_f32 v114, v114, v115
	v_cvt_pk_bf16_f32 v115, v116, v117
	v_add_u32_e32 v116, 0x2000, v145
	v_cvt_pk_bf16_f32 v110, v110, v111
	v_cvt_pk_bf16_f32 v111, v112, v113
	v_cvt_pk_bf16_f32 v102, v102, v103
	v_cvt_pk_bf16_f32 v103, v104, v105
	v_add_u32_e32 v104, 0x4000, v145
	ds_write2_b64 v145, v[82:83], v[84:85] offset0:98 offset1:102
	v_cvt_pk_bf16_f32 v82, v94, v95
	v_cvt_pk_bf16_f32 v83, v96, v97
	v_cvt_pk_bf16_f32 v84, v86, v87
	v_cvt_pk_bf16_f32 v85, v88, v89
	v_cvt_pk_bf16_f32 v70, v70, v71
	v_cvt_pk_bf16_f32 v71, v72, v73
	v_cvt_pk_bf16_f32 v66, v66, v67
	v_cvt_pk_bf16_f32 v67, v68, v69
	ds_write2_b64 v18, v[14:15], v[10:11] offset1:4
	v_add_u32_e32 v10, 0x16e10, v145
	v_cvt_pk_bf16_f32 v6, v6, v7
	v_cvt_pk_bf16_f32 v7, v8, v9
	v_cvt_pk_bf16_f32 v2, v2, v3
	v_cvt_pk_bf16_f32 v3, v4, v5
	v_cmp_gt_i32_e32 vcc, 64, v143
	ds_write2_b64 v145, v[126:127], v[122:123] offset0:66 offset1:70
	ds_write2_b64 v116, v[118:119], v[114:115] offset0:98 offset1:102
	ds_write2_b64 v104, v[110:111], v[102:103] offset0:130 offset1:134
	ds_write2_b64 v116, v[82:83], v[84:85] offset0:130 offset1:134
	ds_write2_b64 v104, v[70:71], v[66:67] offset0:162 offset1:166
	ds_write2_b64 v10, v[6:7], v[2:3] offset1:4
	s_lshl_b32 s98, s24, 7
	v_lshl_or_b32 v82, v0, 3, s98
	v_ashrrev_i32_e32 v83, 31, v82
	v_lshlrev_b64 v[22:23], 2, v[82:83]
	v_lshl_add_u64 v[2:3], s[14:15], 0, v[22:23]
	v_lshl_add_u64 v[10:11], s[88:89], 0, v[22:23]
	global_load_dwordx4 v[6:9], v[2:3], off offset:16
	global_load_dwordx4 v[38:41], v[2:3], off
	s_nop 0
	global_load_dwordx4 v[2:5], v[10:11], off offset:16
	global_load_dwordx4 v[34:37], v[10:11], off
	v_lshl_add_u64 v[10:11], s[90:91], 0, v[22:23]
	v_lshl_add_u64 v[18:19], s[26:27], 0, v[22:23]
	global_load_dwordx4 v[14:17], v[10:11], off offset:16
	global_load_dwordx4 v[46:49], v[10:11], off
	s_nop 0
	global_load_dwordx4 v[10:13], v[18:19], off offset:16
	global_load_dwordx4 v[42:45], v[18:19], off
	v_lshl_add_u64 v[18:19], s[62:63], 0, v[22:23]
	v_lshl_add_u64 v[24:25], s[0:1], 0, v[22:23]
	global_load_dwordx4 v[26:29], v[18:19], off offset:16
	global_load_dwordx4 v[58:61], v[18:19], off
	s_nop 0
	global_load_dwordx4 v[18:21], v[24:25], off offset:16
	global_load_dwordx4 v[50:53], v[24:25], off
	v_lshl_add_u64 v[24:25], s[40:41], 0, v[22:23]
	v_lshl_add_u64 v[54:55], s[4:5], 0, v[22:23]
	global_load_dwordx4 v[30:33], v[24:25], off offset:16
	global_load_dwordx4 v[62:65], v[24:25], off
	s_nop 0
	global_load_dwordx4 v[22:25], v[54:55], off offset:16
	s_nop 0
	global_load_dwordx4 v[54:57], v[54:55], off
	s_and_saveexec_b64 s[42:43], vcc
	s_cbranch_execz .LBB0_400
	v_lshlrev_b32_e32 v206, 3, v144
	v_and_b32_e32 v210, 0xf8, v206
	v_mov_b32_e32 v209, 0
	s_cmpk_gt_i32 s25, 0xff
	v_cmp_gt_u32_e64 s[10:11], 32, v143
	v_mov_b32_e32 v208, 0
	v_mov_b32_e32 v207, 0
	v_mov_b32_e32 v206, 0
	s_cbranch_scc1 .LBB0_399
	s_and_b32 s28, s25, 7
	s_cmp_lg_u32 s28, 0
	s_cselect_b64 s[28:29], -1, 0
	v_cmp_lt_u32_e32 vcc, 31, v143
	s_and_b64 s[28:29], s[28:29], s[10:11]
	v_mov_b32_e32 v206, 0
	v_mov_b32_e32 v207, 0
	v_mov_b32_e32 v208, 0
	v_mov_b32_e32 v209, 0
	s_and_saveexec_b64 s[10:11], s[28:29]
	s_cbranch_execz .LBB0_395
	s_lshl_b32 s28, s25, 1
	s_add_i32 s28, s28, -1
	v_readlane_b32 s44, v252, 20
	s_mul_hi_i32 s29, s28, 0x2c00
	s_mulk_i32 s28, 0x2c00
	v_readlane_b32 s56, v252, 32
	v_readlane_b32 s57, v252, 33
	s_add_u32 s30, s56, s28
	s_addc_u32 s31, s57, s29
	s_lshl_b64 s[28:29], s[6:7], 1
	s_add_u32 s28, s30, s28
	s_addc_u32 s29, s31, s29
	v_lshlrev_b32_e32 v211, 1, v210
	global_load_dwordx4 v[206:209], v211, s[28:29]
	v_readlane_b32 s45, v252, 21
	v_readlane_b32 s46, v252, 22
	v_readlane_b32 s47, v252, 23
	v_readlane_b32 s48, v252, 24
	v_readlane_b32 s49, v252, 25
	v_readlane_b32 s50, v252, 26
	v_readlane_b32 s51, v252, 27
	v_readlane_b32 s52, v252, 28
	v_readlane_b32 s53, v252, 29
	v_readlane_b32 s54, v252, 30
	v_readlane_b32 s55, v252, 31
	v_readlane_b32 s58, v252, 34
	v_readlane_b32 s59, v252, 35
;   __device__ __forceinline__ void operator()(const f32x4 (&acc)[2][2][4][2], int pm, int pn, int wr_, int wc_, int fr_, int fq_, bf16_t* shm, int tid) const {
;     ...
;     if (tid < 64) {
;       const int after = tid >> 5, c = (tid & 31) * 8;
;       u32x4 hv = {0, 0, 0, 0};
;       if (pm < 256) {
;         if (!after && (pm & 7) != 0) hv = *(const u32x4*)(HU + (long)((pm - 1) * 2 + 1) * 5632 + pn * 256 + c);
;         if (after && ((pm + 1) & 7) != 0) hv = *(const u32x4*)(HU + (long)((pm + 1) * 2) * 5632 + pn * 256 + c);
;       }
;       *(u32x4*)(Us + (after ? 257 : 0) * USTR + c) = hv;
.LBB0_395:
	s_or_b64 exec, exec, s[10:11]
	s_and_saveexec_b64 s[10:11], vcc
	s_cbranch_execz .LBB0_398
	s_add_i32 s25, s25, 1
	s_and_b32 s28, s25, 7
	s_cmp_eq_u32 s28, 0
	s_cbranch_scc1 .LBB0_398
	v_readlane_b32 s44, v252, 20
	s_lshl_b32 s28, s25, 1
	s_mulk_i32 s25, 0x5800
	v_readlane_b32 s56, v252, 32
	s_mul_hi_u32 s28, s28, 0x2c00
	v_readlane_b32 s57, v252, 33
	s_add_u32 s25, s56, s25
	s_addc_u32 s28, s57, s28
	s_lshl_b64 s[6:7], s[6:7], 1
	s_add_u32 s6, s25, s6
	s_addc_u32 s7, s28, s7
	v_lshlrev_b32_e32 v211, 1, v210
	global_load_dwordx4 v[206:209], v211, s[6:7]
	v_readlane_b32 s45, v252, 21
	v_readlane_b32 s46, v252, 22
	v_readlane_b32 s47, v252, 23
	v_readlane_b32 s48, v252, 24
	v_readlane_b32 s49, v252, 25
	v_readlane_b32 s50, v252, 26
	v_readlane_b32 s51, v252, 27
	v_readlane_b32 s52, v252, 28
	v_readlane_b32 s53, v252, 29
	v_readlane_b32 s54, v252, 30
	v_readlane_b32 s55, v252, 31
	v_readlane_b32 s58, v252, 34
	v_readlane_b32 s59, v252, 35
